# hyena job loop: next job index fetched one job ahead, no full store drain at the loop top (on top of the XCD job placement)
# speedup vs baseline: 1.0504x; 1.0504x over previous
; #define TIDX(p) ((p).wv * 64 + (int)__builtin_amdgcn_mbcnt_hi(~0u, __builtin_amdgcn_mbcnt_lo(~0u, 0u)))
;     ...
;   unsigned* cnt = (unsigned*)(p.ws + OFF_CNT) + slot;
;   const int nj = (mode & 2) ? ((l == 0) ? 1536 : 768) : 0;
;   while (true) {
;     __syncthreads();
;     if (TIDX(p) == 0) sjob = (int)atomicAdd(cnt, 1u);
;     __syncthreads();
;     const int j = sjob;
.LBB0_514:
	v_readlane_b32 s4, v255, 20
	v_readlane_b32 s5, v255, 21
	s_lshl_b64 s[0:1], s[4:5], 2
	v_readlane_b32 s2, v253, 35
	v_readlane_b32 s3, v253, 36
	s_add_u32 s0, s2, s0
	s_addc_u32 s1, s3, s1
	v_writelane_b32 v255, s0, 27
	v_readlane_b32 s2, v253, 53
	v_readlane_b32 s3, v253, 54
	v_writelane_b32 v255, s1, 28
	s_and_b64 s[0:1], s[46:47], exec
	s_mul_i32 s1, s4, 0xc00000
	s_cselect_b32 s60, s81, 0x300
	s_mul_hi_i32 s0, s4, 0xc00000
	s_add_u32 s1, s2, s1
	v_writelane_b32 v255, s1, 10
	s_addc_u32 s0, s3, s0
	v_writelane_b32 v255, s0, 22
	s_mul_i32 s73, s4, 0x900
	v_sub_u32_e32 v0, 0, v211
	v_readlane_b32 s0, v255, 7
	s_mul_i32 s61, s4, 0x1b00
	s_mul_i32 s74, s4, 0xffffee00
	v_cmp_eq_u32_e64 s[68:69], s0, v0
	s_ashr_i32 s0, s73, 31
	v_writelane_b32 v255, s0, 15
	s_mov_b32 s83, s70
	s_ashr_i32 s75, s70, 31
	s_mul_i32 s76, s4, 0xfffffd00
	s_mul_i32 s77, s4, 0xffffeb00
	s_and_saveexec_b64 s[4:5], s[68:69]
	v_mov_b32_e32 v2, 1
	v_readlane_b32 s0, v255, 27
	v_readlane_b32 s1, v255, 28
	s_nop 4
	global_atomic_add v215, v1, v2, s[0:1] sc0
	s_or_b64 exec, exec, s[4:5]
	s_branch .LBB0_517

; #define TIDX(p) ((p).wv * 64 + (int)__builtin_amdgcn_mbcnt_hi(~0u, __builtin_amdgcn_mbcnt_lo(~0u, 0u)))
;     ...
;   while (true) {
;     __syncthreads();
;     if (TIDX(p) == 0) sjob = (int)atomicAdd(cnt, 1u);
;     __syncthreads();
;     const int j = sjob;
;     if (j >= nj) break;
.LBB0_517:
	s_waitcnt lgkmcnt(0)
	s_barrier
	s_and_saveexec_b64 s[4:5], s[68:69]
	s_cbranch_execz .LBB0_521
	s_waitcnt vmcnt(0)
	v_readfirstlane_b32 s0, v215
	v_mov_b32_e32 v2, 0x21000
	s_nop 0
	v_mov_b32_e32 v0, s0
	ds_write_b32 v2, v0
	v_mov_b32_e32 v2, 1
	v_readlane_b32 s0, v255, 27
	v_readlane_b32 s1, v255, 28
	s_nop 4
	global_atomic_add v215, v1, v2, s[0:1] sc0

;     ...
;     if (j >= nj) break;
;     if (j < 768) { if (EN & 64) hyena_job<2048>(p, l, j, smem); }
;     else { if (EN & 128) hyena_job<256>(p, l, j - 768, smem); }
;   }
.LBB0_602:
	s_waitcnt vmcnt(0)
	s_mov_b64 s[4:5], 0
	v_readlane_b32 s83, v255, 8
